# GEMM epilogue: dword prefetch of rope-table and rmsnorm-partial lines into L1 (G1,G2); attention epilogue gate loads hoisted (FoX at item start, MLA at epilogue start)
# speedup vs baseline: 1.0066x; 1.0066x over previous
.LBB0_494:
	s_or_b32 s10, s9, s90
	s_cmp_ge_i32 s10, s52
	s_cselect_b64 s[12:13], -1, 0
	s_cmp_lt_i32 s10, s57
	s_cselect_b64 s[14:15], -1, 0
	s_and_b64 s[12:13], s[12:13], s[14:15]
	s_and_b64 s[12:13], s[12:13], exec
	s_cselect_b32 s9, 2, 0
	s_cmp_ge_i32 s10, s53
	s_cselect_b32 s11, s9, 1
	s_or_b32 s9, s10, 0x80
	s_cmp_ge_i32 s9, s52
	s_cselect_b64 s[12:13], -1, 0
	s_cmp_lt_i32 s9, s57
	s_cselect_b64 s[14:15], -1, 0
	s_and_b64 s[12:13], s[12:13], s[14:15]
	s_and_b64 s[12:13], s[12:13], exec
	s_cselect_b32 s12, 2, 0
	s_cmp_ge_i32 s9, s53
	s_cselect_b32 s12, s12, 1
	s_or_b32 s13, s11, s12
	s_cmp_eq_u32 s13, 1
	s_cselect_b64 s[64:65], -1, 0
	v_lshl_add_u32 v222, s8, 8, v228
	s_and_b64 s[8:9], s[64:65], exec
	s_cselect_b32 s8, s36, 0
	v_or_b32_e32 v0, s8, v231
	s_cselect_b32 s9, s68, s35
	s_cselect_b32 s8, s33, s34
	v_lshlrev_b32_e32 v0, 2, v0
	s_cselect_b32 s15, s70, s61
	s_cselect_b32 s14, s69, s60
	s_cmp_lg_u32 s13, 0
	v_lshl_add_u64 v[220:221], s[8:9], 0, v[0:1]
	s_cselect_b64 s[8:9], -1, 0
	s_cmp_eq_u32 s13, 0
	v_lshl_add_u64 v[226:227], s[14:15], 0, v[0:1]
	s_cbranch_scc1 .LBB0_496
	s_and_b64 s[14:15], s[64:65], exec
	v_and_b32_e32 v0, 0x7cf, v222
	s_cselect_b32 s13, 5, 4
	v_lshlrev_b32_e32 v0, s13, v0
	v_lshlrev_b32_e32 v0, 2, v0
	v_lshl_add_u64 v[2:3], v[220:221], 0, v[0:1]
	v_lshl_add_u64 v[4:5], v[226:227], 0, v[0:1]
	global_load_dwordx4 v[18:21], v[2:3], off
	global_load_dwordx4 v[186:189], v[4:5], off
	s_lshl_b32 s100, 64, s13
	s_mov_b32 s101, 0
	v_mov_b64_e32 v[12:13], v[2:3]
	v_mov_b64_e32 v[14:15], v[4:5]
	v_lshl_add_u64 v[12:13], v[12:13], 0, s[100:101]
	v_lshl_add_u64 v[14:15], v[14:15], 0, s[100:101]
	global_load_dword v16, v[12:13], off
	global_load_dword v16, v[14:15], off
	v_lshl_add_u64 v[12:13], v[12:13], 0, s[100:101]
	v_lshl_add_u64 v[14:15], v[14:15], 0, s[100:101]
	global_load_dword v16, v[12:13], off
	global_load_dword v16, v[14:15], off
	v_lshl_add_u64 v[12:13], v[12:13], 0, s[100:101]
	v_lshl_add_u64 v[14:15], v[14:15], 0, s[100:101]
	global_load_dword v16, v[12:13], off
	global_load_dword v16, v[14:15], off
	s_branch .LBB0_497

.LBB0_536:
	v_pk_mul_f32 v[58:59], v[128:129], v[152:153]
	v_pk_mul_f32 v[134:135], v[126:127], v[150:151]
	v_pk_mul_f32 v[136:137], v[128:129], v[16:17]
	v_pk_mul_f32 v[138:139], v[126:127], v[14:15]
	v_pk_fma_f32 v[58:59], v[132:133], v[16:17], v[58:59] neg_lo:[0,0,1] neg_hi:[0,0,1]
	v_pk_fma_f32 v[134:135], v[130:131], v[14:15], v[134:135] neg_lo:[0,0,1] neg_hi:[0,0,1]
	v_pk_fma_f32 v[136:137], v[132:133], v[152:153], v[136:137]
	v_pk_fma_f32 v[138:139], v[130:131], v[150:151], v[138:139]
	v_cndmask_b32_e64 v0, v59, v133, s[10:11]
	v_cndmask_b32_e64 v58, v58, v132, s[10:11]
	v_cndmask_b32_e64 v59, v135, v131, s[10:11]
	v_cndmask_b32_e64 v130, v134, v130, s[10:11]
	v_cndmask_b32_e64 v129, v137, v129, s[10:11]
	v_cndmask_b32_e64 v131, v136, v128, s[10:11]
	v_cndmask_b32_e64 v128, v139, v127, s[10:11]
	v_cndmask_b32_e64 v132, v138, v126, s[10:11]
	v_cvt_pk_bf16_f32 v126, v130, v59
	v_cvt_pk_bf16_f32 v127, v58, v0
	v_cvt_pk_bf16_f32 v128, v132, v128
	v_cvt_pk_bf16_f32 v129, v131, v129
	global_store_dwordx4 v[60:61], v[126:129], off offset:256
	s_and_b64 vcc, exec, s[16:17]
	s_nop 0
	v_add_u32_e32 v126, 0x80, v222
	s_cbranch_vccnz .LBB0_538
	s_and_b64 s[66:67], s[64:65], exec
	v_and_b32_e32 v0, 0x7cf, v126
	s_cselect_b32 s39, 5, 4
	v_lshlrev_b32_e32 v0, s39, v0
	v_lshlrev_b32_e32 v0, 2, v0
	v_lshl_add_u64 v[2:3], v[220:221], 0, v[0:1]
	global_load_dwordx4 v[30:33], v[2:3], off
	v_lshl_add_u64 v[2:3], v[226:227], 0, v[0:1]
	global_load_dwordx4 v[186:189], v[2:3], off
	s_lshl_b32 s100, 64, s39
	s_mov_b32 s101, 0
	v_lshl_add_u64 v[4:5], v[220:221], 0, v[0:1]
	v_mov_b64_e32 v[6:7], v[2:3]
	v_lshl_add_u64 v[4:5], v[4:5], 0, s[100:101]
	v_lshl_add_u64 v[6:7], v[6:7], 0, s[100:101]
	global_load_dword v8, v[4:5], off
	global_load_dword v8, v[6:7], off
	v_lshl_add_u64 v[4:5], v[4:5], 0, s[100:101]
	v_lshl_add_u64 v[6:7], v[6:7], 0, s[100:101]
	global_load_dword v8, v[4:5], off
	global_load_dword v8, v[6:7], off
	v_lshl_add_u64 v[4:5], v[4:5], 0, s[100:101]
	v_lshl_add_u64 v[6:7], v[6:7], 0, s[100:101]
	global_load_dword v8, v[4:5], off
	global_load_dword v8, v[6:7], off
	s_waitcnt vmcnt(0)
	v_mov_b64_e32 v[60:61], v[44:45]
	v_mov_b64_e32 v[58:59], v[42:43]
	v_mov_b64_e32 v[56:57], v[40:41]
	v_mov_b64_e32 v[54:55], v[38:39]
	v_mov_b64_e32 v[52:53], v[36:37]
	v_mov_b64_e32 v[50:51], v[34:35]
	v_mov_b64_e32 v[2:3], v[30:31]
	v_mov_b64_e32 v[4:5], v[32:33]
	v_mov_b64_e32 v[6:7], v[34:35]
	v_mov_b64_e32 v[8:9], v[36:37]
	v_mov_b64_e32 v[10:11], v[38:39]
	v_mov_b64_e32 v[12:13], v[40:41]
	v_mov_b64_e32 v[14:15], v[42:43]
	v_mov_b64_e32 v[16:17], v[44:45]
	v_mov_b64_e32 v[48:49], v[32:33]
	v_mov_b64_e32 v[46:47], v[30:31]
	v_mov_b64_e32 v[18:19], v[30:31]
	v_mov_b64_e32 v[20:21], v[32:33]
	v_mov_b64_e32 v[22:23], v[34:35]
	v_mov_b64_e32 v[24:25], v[36:37]
	v_mov_b64_e32 v[26:27], v[38:39]
	v_mov_b64_e32 v[28:29], v[40:41]
	v_mov_b64_e32 v[30:31], v[42:43]
	v_mov_b64_e32 v[32:33], v[44:45]

.LBB0_711:
	v_pk_add_f32 v[34:35], v[110:111], v[110:111] op_sel:[0,1] op_sel_hi:[1,0]
	s_lshl_b64 s[4:5], s[10:11], 22
	v_mov_b32_e32 v35, v34
	s_nop 1
	v_permlane32_swap_b32_e32 v34, v35
	v_add_f32_e32 v34, v34, v35
	v_div_scale_f32 v35, s[10:11], v34, v34, 1.0
	v_rcp_f32_e32 v36, v35
	s_add_u32 s4, s80, s4
	s_addc_u32 s5, s83, s5
	s_add_u32 s4, s4, s38
	v_fma_f32 v37, -v35, v36, 1.0
	v_fmac_f32_e32 v36, v37, v36
	v_div_scale_f32 v37, vcc, 1.0, v34, 1.0
	v_mul_f32_e32 v38, v37, v36
	v_fma_f32 v39, -v35, v38, v37
	s_addc_u32 s5, s5, 0
	v_fmac_f32_e32 v38, v39, v36
	s_add_u32 s6, s22, s38
	v_fma_f32 v35, -v35, v38, v37
	s_addc_u32 s7, s23, 0
	v_div_fmas_f32 v35, v35, v36, v38
	v_div_fixup_f32 v36, v35, v34, 1.0
	v_lshl_add_u64 v[34:35], v[112:113], 1, s[6:7]
	v_lshlrev_b64 v[38:39], 11, v[98:99]
	v_lshlrev_b32_e32 v0, 1, v0
	v_lshl_add_u64 v[42:43], s[4:5], 0, v[38:39]
	v_mul_f32_e32 v38, v18, v36
	v_mul_f32_e32 v39, v19, v36
	v_lshl_add_u64 v[18:19], v[34:35], 0, v[0:1]
	s_mov_b64 s[4:5], 0x1c00
	v_mul_f32_e32 v40, v22, v36
	v_mul_f32_e32 v41, v23, v36
	v_lshl_add_u64 v[22:23], v[18:19], 0, s[4:5]
	s_movk_i32 s4, 0x1000
	v_add_co_u32_e32 v18, vcc, s4, v18
	v_mul_f32_e32 v44, v20, v36
	s_nop 0
	v_addc_co_u32_e32 v19, vcc, 0, v19, vcc
	v_mul_f32_e32 v45, v21, v36
	s_nop 0
	v_permlane32_swap_b32_e32 v38, v40
	v_permlane32_swap_b32_e32 v39, v41
	v_mul_f32_e32 v24, v24, v36
	v_mul_f32_e32 v25, v25, v36
	s_nop 0
	v_permlane32_swap_b32_e32 v44, v24
	v_permlane32_swap_b32_e32 v45, v25
	v_mul_f32_e32 v6, v6, v36
	v_mul_f32_e32 v7, v7, v36
	v_mul_f32_e32 v8, v8, v36
	v_mul_f32_e32 v9, v9, v36
	v_mov_b32_e32 v18, v224
	v_mov_b32_e32 v19, v225
	v_mov_b32_e32 v20, v226
	v_mov_b32_e32 v21, v227
	v_lshlrev_b32_e32 v34, 16, v18
	v_and_b32_e32 v35, 0xffff0000, v18
	v_mul_f32_e32 v18, 0xbfb8aa3b, v34
	v_exp_f32_e32 v18, v18
	s_nop 0
	v_add_f32_e32 v18, 1.0, v18
	v_rcp_f32_e32 v46, v18
	v_mul_f32_e32 v18, 0xbfb8aa3b, v35
	v_exp_f32_e32 v18, v18
	s_nop 0
	v_add_f32_e32 v18, 1.0, v18
	v_rcp_f32_e32 v47, v18
	v_lshlrev_b32_e32 v18, 16, v19
	v_mul_f32_e32 v37, 0xbfb8aa3b, v18
	v_exp_f32_e32 v37, v37
	v_pk_mul_f32 v[34:35], v[46:47], v[34:35]
	v_and_b32_e32 v19, 0xffff0000, v19
	v_pk_mul_f32 v[34:35], v[34:35], v[38:39]
	v_add_f32_e32 v37, 1.0, v37
	v_rcp_f32_e32 v38, v37
	v_mul_f32_e32 v37, 0xbfb8aa3b, v19
	v_exp_f32_e32 v37, v37
	s_nop 0
	v_add_f32_e32 v37, 1.0, v37
	v_rcp_f32_e32 v39, v37
	s_nop 0
	v_pk_mul_f32 v[18:19], v[38:39], v[18:19]
	v_lshlrev_b32_e32 v38, 16, v20
	v_and_b32_e32 v39, 0xffff0000, v20
	v_mul_f32_e32 v20, 0xbfb8aa3b, v38
	v_exp_f32_e32 v20, v20
	v_pk_mul_f32 v[18:19], v[18:19], v[44:45]
	v_add_f32_e32 v20, 1.0, v20
	v_rcp_f32_e32 v44, v20
	v_mul_f32_e32 v20, 0xbfb8aa3b, v39
	v_exp_f32_e32 v20, v20
	s_nop 0
	v_add_f32_e32 v20, 1.0, v20
	v_rcp_f32_e32 v45, v20
	v_lshlrev_b32_e32 v20, 16, v21
	v_mul_f32_e32 v37, 0xbfb8aa3b, v20
	v_exp_f32_e32 v37, v37
	v_pk_mul_f32 v[38:39], v[44:45], v[38:39]
	v_and_b32_e32 v21, 0xffff0000, v21
	v_pk_mul_f32 v[40:41], v[38:39], v[40:41]
	v_add_f32_e32 v37, 1.0, v37
	v_rcp_f32_e32 v38, v37
	v_mul_f32_e32 v37, 0xbfb8aa3b, v21
	v_exp_f32_e32 v37, v37
	v_cvt_pk_bf16_f32 v40, v40, v41
	v_add_f32_e32 v37, 1.0, v37
	v_rcp_f32_e32 v39, v37
	s_nop 0
	v_pk_mul_f32 v[20:21], v[38:39], v[20:21]
	s_nop 0
	v_pk_mul_f32 v[20:21], v[20:21], v[24:25]
	v_cvt_pk_bf16_f32 v38, v34, v35
	v_mul_f32_e32 v34, v26, v36
	v_mul_f32_e32 v24, v30, v36
	v_mul_f32_e32 v35, v27, v36
	v_mul_f32_e32 v25, v31, v36
	v_mul_f32_e32 v26, v28, v36
	v_mul_f32_e32 v27, v29, v36
	s_nop 0
	v_cvt_pk_bf16_f32 v41, v20, v21
	v_mul_f32_e32 v20, v32, v36
	v_cvt_pk_bf16_f32 v39, v18, v19
	v_lshl_add_u64 v[18:19], v[42:43], 0, v[0:1]
	v_mul_f32_e32 v21, v33, v36
	global_store_dwordx4 v[18:19], v[38:41], off offset:1024
	v_permlane32_swap_b32_e32 v34, v24
	v_permlane32_swap_b32_e32 v35, v25
	v_permlane32_swap_b32_e32 v26, v20
	v_permlane32_swap_b32_e32 v27, v21
	v_mov_b32_e32 v28, v228
	v_mov_b32_e32 v29, v229
	v_mov_b32_e32 v30, v230
	v_mov_b32_e32 v31, v231
	v_lshlrev_b32_e32 v32, 16, v28
	v_mul_f32_e32 v0, 0xbfb8aa3b, v32
	v_exp_f32_e32 v0, v0
	v_and_b32_e32 v33, 0xffff0000, v28
	v_lshlrev_b32_e32 v28, 16, v29
	v_and_b32_e32 v29, 0xffff0000, v29
	v_add_f32_e32 v0, 1.0, v0
	v_rcp_f32_e32 v38, v0
	v_mul_f32_e32 v0, 0xbfb8aa3b, v33
	v_exp_f32_e32 v0, v0
	s_nop 0
	v_add_f32_e32 v0, 1.0, v0
	v_rcp_f32_e32 v39, v0
	v_mul_f32_e32 v0, 0xbfb8aa3b, v28
	v_exp_f32_e32 v0, v0
	v_pk_mul_f32 v[32:33], v[38:39], v[32:33]
	s_nop 0
	v_pk_mul_f32 v[32:33], v[32:33], v[34:35]
	v_add_f32_e32 v0, 1.0, v0
	v_rcp_f32_e32 v34, v0
	v_mul_f32_e32 v0, 0xbfb8aa3b, v29
	v_exp_f32_e32 v0, v0
	s_nop 0
	v_add_f32_e32 v0, 1.0, v0
	v_rcp_f32_e32 v35, v0
	s_nop 0
	v_pk_mul_f32 v[28:29], v[34:35], v[28:29]
	s_nop 0
	v_pk_mul_f32 v[26:27], v[28:29], v[26:27]
	v_lshlrev_b32_e32 v28, 16, v30
	v_mul_f32_e32 v0, 0xbfb8aa3b, v28
	v_exp_f32_e32 v0, v0
	v_and_b32_e32 v29, 0xffff0000, v30
	v_add_f32_e32 v0, 1.0, v0
	v_rcp_f32_e32 v34, v0
	v_mul_f32_e32 v0, 0xbfb8aa3b, v29
	v_exp_f32_e32 v0, v0
	s_nop 0
	v_add_f32_e32 v0, 1.0, v0
	v_rcp_f32_e32 v35, v0
	s_nop 0
	v_pk_mul_f32 v[28:29], v[34:35], v[28:29]
	s_nop 0
	v_pk_mul_f32 v[28:29], v[28:29], v[24:25]
	v_lshlrev_b32_e32 v24, 16, v31
	v_mul_f32_e32 v0, 0xbfb8aa3b, v24
	v_exp_f32_e32 v0, v0
	v_and_b32_e32 v25, 0xffff0000, v31
	v_add_f32_e32 v0, 1.0, v0
	v_rcp_f32_e32 v30, v0
	v_mul_f32_e32 v0, 0xbfb8aa3b, v25
	v_exp_f32_e32 v0, v0
	s_nop 0
	v_add_f32_e32 v0, 1.0, v0
	v_rcp_f32_e32 v31, v0
	s_nop 0
	v_pk_mul_f32 v[24:25], v[30:31], v[24:25]
	s_nop 0
	v_pk_mul_f32 v[20:21], v[24:25], v[20:21]
	v_cvt_pk_bf16_f32 v24, v32, v33
	v_cvt_pk_bf16_f32 v25, v26, v27
	v_cvt_pk_bf16_f32 v26, v28, v29
	v_cvt_pk_bf16_f32 v27, v20, v21
	global_store_dwordx4 v[18:19], v[24:27], off offset:1056
	v_mul_f32_e32 v20, v2, v36
	v_mul_f32_e32 v21, v3, v36
	v_mul_f32_e32 v24, v4, v36
	v_mul_f32_e32 v25, v5, v36
	s_nop 0
	v_permlane32_swap_b32_e32 v20, v6
	v_permlane32_swap_b32_e32 v21, v7
	v_permlane32_swap_b32_e32 v24, v8
	v_permlane32_swap_b32_e32 v25, v9
	v_mov_b32_e32 v2, v232
	v_mov_b32_e32 v3, v233
	v_mov_b32_e32 v4, v234
	v_mov_b32_e32 v5, v235
	v_lshlrev_b32_e32 v26, 16, v2
	v_mul_f32_e32 v0, 0xbfb8aa3b, v26
	v_exp_f32_e32 v0, v0
	v_and_b32_e32 v27, 0xffff0000, v2
	v_lshlrev_b32_e32 v2, 16, v3
	v_and_b32_e32 v3, 0xffff0000, v3
	v_add_f32_e32 v0, 1.0, v0
	v_rcp_f32_e32 v28, v0
	v_mul_f32_e32 v0, 0xbfb8aa3b, v27
	v_exp_f32_e32 v0, v0
	s_nop 0
	v_add_f32_e32 v0, 1.0, v0
	v_rcp_f32_e32 v29, v0
	v_mul_f32_e32 v0, 0xbfb8aa3b, v2
	v_exp_f32_e32 v0, v0
	v_pk_mul_f32 v[26:27], v[28:29], v[26:27]
	s_nop 0
	v_pk_mul_f32 v[20:21], v[26:27], v[20:21]
	v_add_f32_e32 v0, 1.0, v0
	v_rcp_f32_e32 v26, v0
	v_mul_f32_e32 v0, 0xbfb8aa3b, v3
	v_exp_f32_e32 v0, v0
	s_nop 0
	v_add_f32_e32 v0, 1.0, v0
	v_rcp_f32_e32 v27, v0
	s_nop 0
	v_pk_mul_f32 v[2:3], v[26:27], v[2:3]
	s_nop 0
	v_pk_mul_f32 v[24:25], v[2:3], v[24:25]
	v_lshlrev_b32_e32 v2, 16, v4
	v_mul_f32_e32 v0, 0xbfb8aa3b, v2
	v_exp_f32_e32 v0, v0
	v_and_b32_e32 v3, 0xffff0000, v4
	v_add_f32_e32 v0, 1.0, v0
	v_rcp_f32_e32 v26, v0
	v_mul_f32_e32 v0, 0xbfb8aa3b, v3
	v_exp_f32_e32 v0, v0
	s_nop 0
	v_add_f32_e32 v0, 1.0, v0
	v_rcp_f32_e32 v27, v0
	s_nop 0
	v_pk_mul_f32 v[2:3], v[26:27], v[2:3]
	s_nop 0
	v_pk_mul_f32 v[6:7], v[2:3], v[6:7]
	v_lshlrev_b32_e32 v2, 16, v5
	v_mul_f32_e32 v0, 0xbfb8aa3b, v2
	v_exp_f32_e32 v0, v0
	v_and_b32_e32 v3, 0xffff0000, v5
	v_add_f32_e32 v0, 1.0, v0
	v_rcp_f32_e32 v4, v0
	v_mul_f32_e32 v0, 0xbfb8aa3b, v3
	v_exp_f32_e32 v0, v0
	s_nop 0
	v_add_f32_e32 v0, 1.0, v0
	v_rcp_f32_e32 v5, v0
	s_nop 0
	v_pk_mul_f32 v[2:3], v[4:5], v[2:3]
	s_nop 0
	v_pk_mul_f32 v[8:9], v[2:3], v[8:9]
	v_cvt_pk_bf16_f32 v2, v20, v21
	v_cvt_pk_bf16_f32 v3, v24, v25
	v_cvt_pk_bf16_f32 v4, v6, v7
	v_cvt_pk_bf16_f32 v5, v8, v9
	global_store_dwordx4 v[18:19], v[2:5], off offset:1088
	s_nop 0
	v_mul_f32_e32 v20, v10, v36
	v_mul_f32_e32 v10, v12, v36
	v_mul_f32_e32 v21, v11, v36
	v_mul_f32_e32 v11, v13, v36
	v_mul_f32_e32 v8, v14, v36
	v_mul_f32_e32 v9, v15, v36
	v_mul_f32_e32 v6, v16, v36
	v_mul_f32_e32 v7, v17, v36
	s_nop 0
	v_permlane32_swap_b32_e32 v10, v6
	v_permlane32_swap_b32_e32 v11, v7
	v_permlane32_swap_b32_e32 v20, v8
	v_permlane32_swap_b32_e32 v21, v9
	v_mov_b32_e32 v2, v236
	v_mov_b32_e32 v3, v237
	v_mov_b32_e32 v4, v238
	v_mov_b32_e32 v5, v239
	v_lshlrev_b32_e32 v12, 16, v2
	v_mul_f32_e32 v0, 0xbfb8aa3b, v12
	v_exp_f32_e32 v0, v0
	v_and_b32_e32 v13, 0xffff0000, v2
	v_lshlrev_b32_e32 v2, 16, v3
	v_and_b32_e32 v3, 0xffff0000, v3
	v_add_f32_e32 v0, 1.0, v0
	v_rcp_f32_e32 v14, v0
	v_mul_f32_e32 v0, 0xbfb8aa3b, v13
	v_exp_f32_e32 v0, v0
	s_nop 0
	v_add_f32_e32 v0, 1.0, v0
	v_rcp_f32_e32 v15, v0
	v_mul_f32_e32 v0, 0xbfb8aa3b, v2
	v_exp_f32_e32 v0, v0
	v_pk_mul_f32 v[12:13], v[14:15], v[12:13]
	s_nop 0
	v_pk_mul_f32 v[12:13], v[12:13], v[20:21]
	v_add_f32_e32 v0, 1.0, v0
	v_rcp_f32_e32 v14, v0
	v_mul_f32_e32 v0, 0xbfb8aa3b, v3
	v_exp_f32_e32 v0, v0
	s_nop 0
	v_add_f32_e32 v0, 1.0, v0
	v_rcp_f32_e32 v15, v0
	s_nop 0
	v_pk_mul_f32 v[2:3], v[14:15], v[2:3]
	s_nop 0
	v_pk_mul_f32 v[10:11], v[2:3], v[10:11]
	v_lshlrev_b32_e32 v2, 16, v4
	v_mul_f32_e32 v0, 0xbfb8aa3b, v2
	v_exp_f32_e32 v0, v0
	v_and_b32_e32 v3, 0xffff0000, v4
	v_add_f32_e32 v0, 1.0, v0
	v_rcp_f32_e32 v14, v0
	v_mul_f32_e32 v0, 0xbfb8aa3b, v3
	v_exp_f32_e32 v0, v0
	s_nop 0
	v_add_f32_e32 v0, 1.0, v0
	v_rcp_f32_e32 v15, v0
	s_nop 0
	v_pk_mul_f32 v[2:3], v[14:15], v[2:3]
	s_nop 0
	v_pk_mul_f32 v[8:9], v[2:3], v[8:9]
	v_lshlrev_b32_e32 v2, 16, v5
	v_mul_f32_e32 v0, 0xbfb8aa3b, v2
	v_exp_f32_e32 v0, v0
	v_and_b32_e32 v3, 0xffff0000, v5
	v_add_f32_e32 v0, 1.0, v0
	v_rcp_f32_e32 v4, v0
	v_mul_f32_e32 v0, 0xbfb8aa3b, v3
	v_exp_f32_e32 v0, v0
	s_nop 0
	v_add_f32_e32 v0, 1.0, v0
	v_rcp_f32_e32 v5, v0
	s_nop 0
	v_pk_mul_f32 v[2:3], v[4:5], v[2:3]
	s_nop 0
	v_pk_mul_f32 v[6:7], v[2:3], v[6:7]
	v_cvt_pk_bf16_f32 v2, v12, v13
	v_cvt_pk_bf16_f32 v3, v10, v11
	v_cvt_pk_bf16_f32 v4, v8, v9
	v_cvt_pk_bf16_f32 v5, v6, v7
	global_store_dwordx4 v[18:19], v[2:5], off offset:1120

.LBB0_724:
	s_ashr_i32 s10, s8, 3
	s_ashr_i32 s11, s10, 31
	s_lshl_b64 s[4:5], s[10:11], 24
	v_readlane_b32 s6, v254, 23
	v_readlane_b32 s7, v254, 24
	s_add_u32 s22, s6, s4
	s_addc_u32 s23, s7, s5
	s_lshl_b32 s4, s8, 6
	s_and_b32 s4, s4, 0x1c0
	s_lshl_b32 s38, s4, 1
	s_add_u32 s12, s22, s38
	s_addc_u32 s13, s23, 0
	s_add_u32 s4, s12, 0x1000
	s_addc_u32 s5, s13, 0
	v_mov_b32_e32 v14, v244
	s_add_u32 s6, s12, 0x1400
	s_addc_u32 s7, s13, 0
	v_readfirstlane_b32 s9, v14
	s_ashr_i32 s15, s9, 6
	s_lshl_b32 s14, s37, 8
	s_lshl_b32 s16, s15, 5
	v_and_b32_e32 v15, 31, v14
	s_add_i32 s14, s16, s14
	v_or_b32_e32 v98, s14, v15
	v_ashrrev_i32_e32 v99, 31, v98
	v_bfe_u32 v121, v14, 5, 1
	v_lshlrev_b64 v[2:3], 13, v[98:99]
	v_lshl_add_u64 v[2:3], s[12:13], 0, v[2:3]
	v_lshlrev_b32_e32 v100, 4, v121
	v_mov_b32_e32 v101, v1
	v_lshl_add_u64 v[2:3], v[2:3], 0, v[100:101]
	global_load_dwordx4 v[66:69], v[2:3], off offset:3072
	global_load_dwordx4 v[70:73], v[2:3], off offset:3104
	global_load_dwordx4 v[74:77], v[2:3], off offset:3136
	global_load_dwordx4 v[78:81], v[2:3], off offset:3168
	s_mov_b64 s[100:101], 0x1000
	v_lshl_add_u64 v[222:223], v[2:3], 0, s[100:101]
	global_load_dwordx4 v[224:227], v[222:223], off offset:3072
	global_load_dwordx4 v[228:231], v[222:223], off offset:3104
	global_load_dwordx4 v[232:235], v[222:223], off offset:3136
	global_load_dwordx4 v[236:239], v[222:223], off offset:3168
	v_and_b32_e32 v16, 63, v14
	s_andn2_b32 s9, s9, 63
	v_or_b32_e32 v11, 0xfffffdc0, v16
	s_cmp_gt_i32 s15, 8
	s_mov_b64 s[12:13], -1
	s_cbranch_scc0 .LBB0_726
	v_add_u32_e32 v0, s9, v11
	s_mov_b32 s12, 0xaaaaaaab
	v_mul_hi_u32 v4, v0, s12
	v_lshrrev_b32_e32 v2, 3, v4
	v_mad_u64_u32 v[2:3], s[12:13], v2, -12, v[0:1]
	v_lshlrev_b32_e32 v0, 10, v4
	v_and_b32_e32 v0, 0x7e000, v0
	v_lshl_add_u64 v[4:5], s[6:7], 0, v[0:1]
	s_cbranch_execnz .LBB0_728
	s_branch .LBB0_727

.LBB0_868:
	s_or_b32 vcc_lo, s13, s12
	s_cmp_eq_u32 vcc_lo, 1
	v_lshl_add_u32 v222, s44, 8, v232
	s_cselect_b64 s[44:45], -1, 0
	s_and_b64 s[8:9], s[44:45], exec
	s_cselect_b32 s8, s54, 0
	v_or_b32_e32 v0, s8, v235
	s_cselect_b32 s9, s68, s35
	s_cselect_b32 s8, s33, s34
	v_lshlrev_b32_e32 v0, 2, v0
	v_lshl_add_u64 v[218:219], s[8:9], 0, v[0:1]
	s_cselect_b32 s9, s70, s61
	s_cselect_b32 s8, s69, s60
	s_cmp_lg_u32 vcc_lo, 0
	v_lshl_add_u64 v[220:221], s[8:9], 0, v[0:1]
	s_cselect_b64 s[10:11], -1, 0
	s_cmp_eq_u32 vcc_lo, 0
	s_cbranch_scc1 .LBB0_870
	s_and_b64 s[8:9], s[44:45], exec
	v_and_b32_e32 v0, 0x7cf, v222
	s_cselect_b32 s8, 5, 4
	v_lshlrev_b32_e32 v0, s8, v0
	v_lshlrev_b32_e32 v0, 2, v0
	v_lshl_add_u64 v[2:3], v[218:219], 0, v[0:1]
	v_lshl_add_u64 v[4:5], v[220:221], 0, v[0:1]
	global_load_dwordx4 v[18:21], v[2:3], off
	global_load_dwordx4 v[166:169], v[4:5], off
	s_lshl_b32 s100, 64, s8
	s_mov_b32 s101, 0
	v_mov_b64_e32 v[12:13], v[2:3]
	v_mov_b64_e32 v[14:15], v[4:5]
	v_lshl_add_u64 v[12:13], v[12:13], 0, s[100:101]
	v_lshl_add_u64 v[14:15], v[14:15], 0, s[100:101]
	global_load_dword v16, v[12:13], off
	global_load_dword v16, v[14:15], off
	v_lshl_add_u64 v[12:13], v[12:13], 0, s[100:101]
	v_lshl_add_u64 v[14:15], v[14:15], 0, s[100:101]
	global_load_dword v16, v[12:13], off
	global_load_dword v16, v[14:15], off
	v_lshl_add_u64 v[12:13], v[12:13], 0, s[100:101]
	v_lshl_add_u64 v[14:15], v[14:15], 0, s[100:101]
	global_load_dword v16, v[12:13], off
	global_load_dword v16, v[14:15], off
	s_branch .LBB0_871

.LBB0_871:
	v_mov_b64_e32 v[2:3], s[48:49]
	v_mad_i64_i32 v[2:3], s[8:9], v222, s76, v[2:3]
	global_load_dwordx4 v[4:7], v[2:3], off
	global_load_dwordx4 v[8:11], v[2:3], off offset:16
	global_load_dword v16, v[2:3], off offset:32
	global_load_dword v16, v[2:3], off offset:1280
	global_load_dword v16, v[2:3], off offset:1296
	global_load_dword v16, v[2:3], off offset:1312
	global_load_dword v16, v[2:3], off offset:2560
	global_load_dword v16, v[2:3], off offset:2576
	global_load_dword v16, v[2:3], off offset:2592
	global_load_dword v16, v[2:3], off offset:3840
	global_load_dword v16, v[2:3], off offset:3856
	global_load_dword v16, v[2:3], off offset:3872
	s_and_b64 vcc, exec, s[6:7]
	s_waitcnt vmcnt(0)
	v_mov_b32_e32 v12, v4
	v_mov_b32_e32 v13, v8
	v_mov_b32_e32 v8, v5
	v_mov_b32_e32 v4, v6
	v_mov_b32_e32 v5, v10
	v_mov_b32_e32 v10, v7
	v_pk_add_f32 v[6:7], v[12:13], v[8:9]
	v_pk_add_f32 v[4:5], v[4:5], v[10:11]
	s_nop 0
	v_pk_add_f32 v[4:5], v[6:7], v[4:5]
	s_nop 0
	v_pk_add_f32 v[226:227], v[4:5], v[4:5] op_sel:[0,1] op_sel_hi:[1,0]
	s_cbranch_vccnz .LBB0_873
	global_load_dwordx4 v[2:5], v[2:3], off offset:32
	s_waitcnt vmcnt(0)
	v_mov_b32_e32 v6, v3
	v_mov_b32_e32 v7, v4
	v_mov_b32_e32 v3, v5
	v_pk_add_f32 v[2:3], v[6:7], v[2:3]
	s_nop 0
	v_add_f32_e32 v0, v2, v3
	v_add_f32_e32 v226, v226, v0

.LBB0_888:
	v_div_scale_f32 v0, s[10:11], v236, v236, v226
	v_rcp_f32_e32 v59, v0
	s_cmp_eq_u32 s13, 0
	v_fma_f32 v60, -v0, v59, 1.0
	v_fmac_f32_e32 v59, v60, v59
	v_div_scale_f32 v60, vcc, v226, v236, v226
	v_mul_f32_e32 v61, v60, v59
	v_fma_f32 v224, -v0, v61, v60
	v_fmac_f32_e32 v61, v224, v59
	v_fma_f32 v0, -v0, v61, v60
	v_div_fmas_f32 v0, v0, v59, v61
	v_div_fixup_f32 v0, v0, v236, v226
	v_add_f32_e32 v0, 0x358637bd, v0
	v_cmp_gt_f32_e32 vcc, s75, v0
	v_mul_f32_e32 v59, 0x4b800000, v0
	s_nop 0
	v_cndmask_b32_e32 v0, v0, v59, vcc
	v_rsq_f32_e32 v0, v0
	s_nop 0
	v_mul_f32_e32 v59, 0x45800000, v0
	v_cndmask_b32_e32 v60, v0, v59, vcc
	v_div_scale_f32 v0, s[10:11], v236, v236, v230
	v_rcp_f32_e32 v59, v0
	s_nop 0
	v_fma_f32 v61, -v0, v59, 1.0
	v_fmac_f32_e32 v59, v61, v59
	v_div_scale_f32 v61, vcc, v230, v236, v230
	v_mul_f32_e32 v224, v61, v59
	v_fma_f32 v225, -v0, v224, v61
	v_fmac_f32_e32 v224, v225, v59
	v_fma_f32 v0, -v0, v224, v61
	v_div_fmas_f32 v0, v0, v59, v224
	v_div_fixup_f32 v0, v0, v236, v230
	v_add_f32_e32 v0, 0x358637bd, v0
	v_cmp_gt_f32_e32 vcc, s75, v0
	v_mul_f32_e32 v59, 0x4b800000, v0
	v_or_b32_e32 v230, s63, v233
	v_cndmask_b32_e32 v0, v0, v59, vcc
	v_rsq_f32_e32 v0, v0
	v_ashrrev_i32_e32 v231, 31, v230
	v_mul_f32_e32 v59, 0x45800000, v0
	v_cndmask_b32_e32 v0, v0, v59, vcc
	v_div_scale_f32 v59, s[10:11], v236, v236, v228
	v_rcp_f32_e32 v61, v59
	v_pk_mul_f32 v[150:151], v[150:151], v[0:1] op_sel_hi:[1,0]
	v_pk_mul_f32 v[152:153], v[152:153], v[0:1] op_sel_hi:[1,0]
	v_pk_mul_f32 v[142:143], v[142:143], v[0:1] op_sel_hi:[1,0]
	v_fma_f32 v224, -v59, v61, 1.0
	v_fmac_f32_e32 v61, v224, v61
	v_div_scale_f32 v224, vcc, v228, v236, v228
	v_mul_f32_e32 v225, v224, v61
	v_fma_f32 v226, -v59, v225, v224
	v_fmac_f32_e32 v225, v226, v61
	v_fma_f32 v59, -v59, v225, v224
	v_div_fmas_f32 v59, v59, v61, v225
	v_div_fixup_f32 v59, v59, v236, v228
	v_add_f32_e32 v59, 0x358637bd, v59
	v_cmp_gt_f32_e32 vcc, s75, v59
	v_mul_f32_e32 v61, 0x4b800000, v59
	v_pk_mul_f32 v[144:145], v[144:145], v[0:1] op_sel_hi:[1,0]
	v_cndmask_b32_e32 v59, v59, v61, vcc
	v_rsq_f32_e32 v59, v59
	v_pk_mul_f32 v[146:147], v[146:147], v[0:1] op_sel_hi:[1,0]
	v_pk_mul_f32 v[148:149], v[148:149], v[0:1] op_sel_hi:[1,0]
	v_mul_f32_e32 v61, 0x45800000, v59
	v_cndmask_b32_e32 v226, v59, v61, vcc
	v_div_scale_f32 v59, s[10:11], v236, v236, v58
	v_rcp_f32_e32 v61, v59
	s_cselect_b64 s[10:11], -1, 0
	s_cmp_eq_u32 s12, 0
	s_cselect_b64 s[12:13], -1, 0
	v_fma_f32 v224, -v59, v61, 1.0
	v_fmac_f32_e32 v61, v224, v61
	v_div_scale_f32 v224, vcc, v58, v236, v58
	v_mul_f32_e32 v225, v224, v61
	v_fma_f32 v228, -v59, v225, v224
	v_fmac_f32_e32 v225, v228, v61
	v_fma_f32 v59, -v59, v225, v224
	v_div_fmas_f32 v59, v59, v61, v225
	v_div_fixup_f32 v58, v59, v236, v58
	v_add_f32_e32 v58, 0x358637bd, v58
	v_cmp_gt_f32_e32 vcc, s75, v58
	v_mul_f32_e32 v59, 0x4b800000, v58
	v_pk_mul_f32 v[198:199], v[198:199], v[60:61] op_sel_hi:[1,0]
	v_cndmask_b32_e32 v58, v58, v59, vcc
	v_rsq_f32_e32 v58, v58
	v_pk_mul_f32 v[202:203], v[202:203], v[60:61] op_sel_hi:[1,0]
	v_pk_mul_f32 v[200:201], v[200:201], v[60:61] op_sel_hi:[1,0]
	v_pk_mul_f32 v[240:241], v[166:167], v[198:199]
	v_pk_mul_f32 v[246:247], v[198:199], v[2:3]
	v_pk_mul_f32 v[204:205], v[204:205], v[60:61] op_sel_hi:[1,0]
	v_pk_mul_f32 v[238:239], v[168:169], v[200:201]
	v_pk_fma_f32 v[240:241], v[202:203], v[2:3], v[240:241] neg_lo:[0,0,1] neg_hi:[0,0,1]
	v_pk_mul_f32 v[242:243], v[200:201], v[4:5]
	v_pk_fma_f32 v[246:247], v[166:167], v[202:203], v[246:247]
	v_mul_f32_e32 v59, 0x45800000, v58
	v_pk_fma_f32 v[238:239], v[204:205], v[4:5], v[238:239] neg_lo:[0,0,1] neg_hi:[0,0,1]
	v_pk_fma_f32 v[242:243], v[168:169], v[204:205], v[242:243]
	v_cndmask_b32_e64 v203, v241, v203, s[10:11]
	v_cndmask_b32_e64 v202, v240, v202, s[10:11]
	v_cndmask_b32_e64 v199, v247, v199, s[10:11]
	v_cndmask_b32_e64 v198, v246, v198, s[10:11]
	v_cndmask_b32_e32 v58, v58, v59, vcc
	v_cndmask_b32_e64 v59, v239, v205, s[10:11]
	v_cndmask_b32_e64 v61, v238, v204, s[10:11]
	v_cndmask_b32_e64 v204, v243, v201, s[10:11]
	v_cndmask_b32_e64 v205, v242, v200, s[10:11]
	v_cvt_pk_bf16_f32 v200, v202, v203
	v_cvt_pk_bf16_f32 v202, v198, v199
	v_mad_i64_i32 v[198:199], vcc, v222, s64, 0
	v_cvt_pk_bf16_f32 v203, v205, v204
	v_lshl_add_u64 v[204:205], v[198:199], 1, s[36:37]
	v_lshlrev_b64 v[198:199], 1, v[230:231]
	v_cvt_pk_bf16_f32 v201, v61, v59
	v_lshl_add_u64 v[204:205], v[204:205], 0, v[198:199]
	v_pk_mul_f32 v[186:187], v[186:187], v[60:61] op_sel_hi:[1,0]
	v_pk_mul_f32 v[188:189], v[188:189], v[60:61] op_sel_hi:[1,0]
	v_pk_mul_f32 v[182:183], v[182:183], v[60:61] op_sel_hi:[1,0]
	v_pk_mul_f32 v[60:61], v[184:185], v[60:61] op_sel_hi:[1,0]
	global_store_dwordx4 v[204:205], v[200:203], off
	v_pk_mul_f32 v[184:185], v[168:169], v[60:61]
	v_pk_mul_f32 v[230:231], v[182:183], v[2:3]
	v_pk_mul_f32 v[200:201], v[166:167], v[182:183]
	v_pk_mul_f32 v[202:203], v[60:61], v[4:5]
	v_pk_fma_f32 v[200:201], v[186:187], v[2:3], v[200:201] neg_lo:[0,0,1] neg_hi:[0,0,1]
	v_pk_fma_f32 v[184:185], v[188:189], v[4:5], v[184:185] neg_lo:[0,0,1] neg_hi:[0,0,1]
	v_pk_fma_f32 v[230:231], v[166:167], v[186:187], v[230:231]
	v_pk_fma_f32 v[202:203], v[168:169], v[188:189], v[202:203]
	v_cndmask_b32_e64 v59, v185, v189, s[12:13]
	v_cndmask_b32_e64 v184, v184, v188, s[12:13]
	v_cndmask_b32_e64 v185, v201, v187, s[12:13]
	v_cndmask_b32_e64 v186, v200, v186, s[12:13]
	v_cndmask_b32_e64 v61, v203, v61, s[12:13]
	v_cndmask_b32_e64 v60, v202, v60, s[12:13]
	v_cndmask_b32_e64 v187, v231, v183, s[12:13]
	v_cndmask_b32_e64 v188, v230, v182, s[12:13]
	v_cvt_pk_bf16_f32 v182, v186, v185
	v_cvt_pk_bf16_f32 v183, v184, v59
	v_cvt_pk_bf16_f32 v184, v188, v187
	v_cvt_pk_bf16_f32 v185, v60, v61
	v_pk_mul_f32 v[170:171], v[170:171], v[226:227] op_sel_hi:[1,0]
	global_store_dwordx4 v[204:205], v[182:185], off offset:256
	v_pk_mul_f32 v[60:61], v[178:179], v[226:227] op_sel_hi:[1,0]
	v_pk_mul_f32 v[172:173], v[172:173], v[226:227] op_sel_hi:[1,0]
	v_pk_mul_f32 v[182:183], v[174:175], v[170:171]
	v_pk_mul_f32 v[178:179], v[180:181], v[226:227] op_sel_hi:[1,0]
	v_pk_mul_f32 v[180:181], v[176:177], v[172:173]
	v_pk_fma_f32 v[182:183], v[60:61], v[6:7], v[182:183] neg_lo:[0,0,1] neg_hi:[0,0,1]
	v_pk_mul_f32 v[186:187], v[170:171], v[6:7]
	v_pk_fma_f32 v[180:181], v[178:179], v[8:9], v[180:181] neg_lo:[0,0,1] neg_hi:[0,0,1]
	v_pk_mul_f32 v[184:185], v[172:173], v[8:9]
	v_pk_fma_f32 v[186:187], v[174:175], v[60:61], v[186:187]
	v_cndmask_b32_e64 v61, v183, v61, s[10:11]
	v_cndmask_b32_e64 v60, v182, v60, s[10:11]
	v_pk_fma_f32 v[184:185], v[176:177], v[178:179], v[184:185]
	v_cndmask_b32_e64 v178, v180, v178, s[10:11]
	v_cndmask_b32_e64 v180, v186, v170, s[10:11]
	v_cvt_pk_bf16_f32 v170, v60, v61
	v_mad_i64_i32 v[60:61], vcc, v223, s64, 0
	v_cndmask_b32_e64 v59, v181, v179, s[10:11]
	v_cndmask_b32_e64 v173, v185, v173, s[10:11]
	v_cndmask_b32_e64 v179, v184, v172, s[10:11]
	v_cndmask_b32_e64 v172, v187, v171, s[10:11]
	v_lshl_add_u64 v[60:61], v[60:61], 1, s[36:37]
	v_cvt_pk_bf16_f32 v171, v178, v59
	v_cvt_pk_bf16_f32 v172, v180, v172
	v_cvt_pk_bf16_f32 v173, v179, v173
	v_lshl_add_u64 v[60:61], v[60:61], 0, v[198:199]
	v_pk_mul_f32 v[158:159], v[158:159], v[226:227] op_sel_hi:[1,0]
	v_pk_mul_f32 v[160:161], v[160:161], v[226:227] op_sel_hi:[1,0]
	global_store_dwordx4 v[60:61], v[170:173], off
	v_pk_mul_f32 v[162:163], v[162:163], v[226:227] op_sel_hi:[1,0]
	v_pk_mul_f32 v[164:165], v[164:165], v[226:227] op_sel_hi:[1,0]
	v_pk_mul_f32 v[170:171], v[176:177], v[160:161]
	v_pk_mul_f32 v[172:173], v[174:175], v[158:159]
	v_pk_mul_f32 v[178:179], v[160:161], v[8:9]
	v_pk_mul_f32 v[180:181], v[158:159], v[6:7]
	v_pk_fma_f32 v[172:173], v[162:163], v[6:7], v[172:173] neg_lo:[0,0,1] neg_hi:[0,0,1]
	v_pk_fma_f32 v[170:171], v[164:165], v[8:9], v[170:171] neg_lo:[0,0,1] neg_hi:[0,0,1]
	v_pk_fma_f32 v[180:181], v[174:175], v[162:163], v[180:181]
	v_pk_fma_f32 v[178:179], v[176:177], v[164:165], v[178:179]
	v_cndmask_b32_e64 v59, v171, v165, s[12:13]
	v_cndmask_b32_e64 v164, v170, v164, s[12:13]
	v_cndmask_b32_e64 v163, v173, v163, s[12:13]
	v_cndmask_b32_e64 v162, v172, v162, s[12:13]
	v_cndmask_b32_e64 v161, v179, v161, s[12:13]
	v_cndmask_b32_e64 v165, v178, v160, s[12:13]
	v_cndmask_b32_e64 v160, v181, v159, s[12:13]
	v_cndmask_b32_e64 v170, v180, v158, s[12:13]
	v_cvt_pk_bf16_f32 v158, v162, v163
	v_cvt_pk_bf16_f32 v159, v164, v59
	v_cvt_pk_bf16_f32 v160, v170, v160
	v_cvt_pk_bf16_f32 v161, v165, v161
	global_store_dwordx4 v[60:61], v[158:161], off offset:256
	v_pk_mul_f32 v[60:61], v[154:155], v[0:1] op_sel_hi:[1,0]
	v_pk_mul_f32 v[154:155], v[156:157], v[0:1] op_sel_hi:[1,0]
	v_pk_mul_f32 v[158:159], v[190:191], v[150:151]
	v_pk_mul_f32 v[156:157], v[192:193], v[152:153]
	v_pk_fma_f32 v[158:159], v[60:61], v[10:11], v[158:159] neg_lo:[0,0,1] neg_hi:[0,0,1]
	v_pk_mul_f32 v[162:163], v[150:151], v[10:11]
	v_pk_fma_f32 v[156:157], v[154:155], v[12:13], v[156:157] neg_lo:[0,0,1] neg_hi:[0,0,1]
	v_pk_mul_f32 v[160:161], v[152:153], v[12:13]
	v_pk_fma_f32 v[162:163], v[190:191], v[60:61], v[162:163]
	v_cndmask_b32_e64 v61, v159, v61, s[10:11]
	v_cndmask_b32_e64 v60, v158, v60, s[10:11]
	v_pk_fma_f32 v[160:161], v[192:193], v[154:155], v[160:161]
	v_cndmask_b32_e64 v154, v156, v154, s[10:11]
	v_cndmask_b32_e64 v156, v162, v150, s[10:11]
	v_cvt_pk_bf16_f32 v150, v60, v61
	v_mad_i64_i32 v[60:61], vcc, v227, s64, 0
	v_cndmask_b32_e64 v59, v157, v155, s[10:11]
	v_cndmask_b32_e64 v153, v161, v153, s[10:11]
	v_cndmask_b32_e64 v155, v160, v152, s[10:11]
	v_cndmask_b32_e64 v152, v163, v151, s[10:11]
	v_lshl_add_u64 v[60:61], v[60:61], 1, s[36:37]
	v_cvt_pk_bf16_f32 v151, v154, v59
	v_cvt_pk_bf16_f32 v152, v156, v152
	v_cvt_pk_bf16_f32 v153, v155, v153
	v_lshl_add_u64 v[60:61], v[60:61], 0, v[198:199]
	global_store_dwordx4 v[60:61], v[150:153], off
	v_pk_mul_f32 v[154:155], v[144:145], v[12:13]
	v_pk_mul_f32 v[156:157], v[142:143], v[10:11]
	v_pk_mul_f32 v[150:151], v[192:193], v[144:145]
	v_pk_mul_f32 v[152:153], v[190:191], v[142:143]
	v_pk_fma_f32 v[150:151], v[148:149], v[12:13], v[150:151] neg_lo:[0,0,1] neg_hi:[0,0,1]
	v_pk_fma_f32 v[152:153], v[146:147], v[10:11], v[152:153] neg_lo:[0,0,1] neg_hi:[0,0,1]
	v_pk_fma_f32 v[156:157], v[190:191], v[146:147], v[156:157]
	v_pk_fma_f32 v[154:155], v[192:193], v[148:149], v[154:155]
	v_cndmask_b32_e64 v0, v151, v149, s[12:13]
	v_cndmask_b32_e64 v59, v150, v148, s[12:13]
	v_cndmask_b32_e64 v147, v153, v147, s[12:13]
	v_cndmask_b32_e64 v146, v152, v146, s[12:13]
	v_cndmask_b32_e64 v145, v155, v145, s[12:13]
	v_cndmask_b32_e64 v148, v154, v144, s[12:13]
	v_cndmask_b32_e64 v144, v157, v143, s[12:13]
	v_cndmask_b32_e64 v149, v156, v142, s[12:13]
	v_cvt_pk_bf16_f32 v142, v146, v147
	v_cvt_pk_bf16_f32 v143, v59, v0
	v_cvt_pk_bf16_f32 v144, v149, v144
	v_cvt_pk_bf16_f32 v145, v148, v145
	v_pk_mul_f32 v[134:135], v[134:135], v[58:59] op_sel_hi:[1,0]
	global_store_dwordx4 v[60:61], v[142:145], off offset:256
	v_pk_mul_f32 v[60:61], v[138:139], v[58:59] op_sel_hi:[1,0]
	v_pk_mul_f32 v[136:137], v[136:137], v[58:59] op_sel_hi:[1,0]
	v_pk_mul_f32 v[142:143], v[194:195], v[134:135]
	v_pk_mul_f32 v[138:139], v[140:141], v[58:59] op_sel_hi:[1,0]
	v_pk_mul_f32 v[140:141], v[196:197], v[136:137]
	v_pk_fma_f32 v[142:143], v[14:15], v[60:61], v[142:143] neg_lo:[0,0,1] neg_hi:[0,0,1]
	v_pk_mul_f32 v[146:147], v[14:15], v[134:135]
	v_pk_fma_f32 v[140:141], v[16:17], v[138:139], v[140:141] neg_lo:[0,0,1] neg_hi:[0,0,1]
	v_pk_mul_f32 v[144:145], v[16:17], v[136:137]
	v_pk_fma_f32 v[146:147], v[194:195], v[60:61], v[146:147]
	v_cndmask_b32_e64 v61, v143, v61, s[10:11]
	v_cndmask_b32_e64 v60, v142, v60, s[10:11]
	v_pk_fma_f32 v[144:145], v[196:197], v[138:139], v[144:145]
	v_cndmask_b32_e64 v0, v141, v139, s[10:11]
	v_cndmask_b32_e64 v139, v146, v134, s[10:11]
	v_cvt_pk_bf16_f32 v134, v60, v61
	v_mad_i64_i32 v[60:61], vcc, v229, s64, 0
	v_cndmask_b32_e64 v59, v140, v138, s[10:11]
	v_cndmask_b32_e64 v137, v145, v137, s[10:11]
	v_cndmask_b32_e64 v138, v144, v136, s[10:11]
	v_cndmask_b32_e64 v136, v147, v135, s[10:11]
	v_lshl_add_u64 v[60:61], v[60:61], 1, s[36:37]
	v_cvt_pk_bf16_f32 v135, v59, v0
	v_cvt_pk_bf16_f32 v136, v139, v136
	v_cvt_pk_bf16_f32 v137, v138, v137
	v_lshl_add_u64 v[138:139], v[60:61], 0, v[198:199]
	v_pk_mul_f32 v[60:61], v[130:131], v[58:59] op_sel_hi:[1,0]
	v_pk_mul_f32 v[130:131], v[132:133], v[58:59] op_sel_hi:[1,0]
	v_pk_mul_f32 v[126:127], v[126:127], v[58:59] op_sel_hi:[1,0]
	v_pk_mul_f32 v[58:59], v[128:129], v[58:59] op_sel_hi:[1,0]
	global_store_dwordx4 v[138:139], v[134:137], off
	v_pk_mul_f32 v[128:129], v[196:197], v[58:59]
	v_pk_mul_f32 v[132:133], v[194:195], v[126:127]
	v_pk_mul_f32 v[134:135], v[16:17], v[58:59]
	v_pk_mul_f32 v[136:137], v[14:15], v[126:127]
	v_pk_fma_f32 v[132:133], v[14:15], v[60:61], v[132:133] neg_lo:[0,0,1] neg_hi:[0,0,1]
	v_pk_fma_f32 v[128:129], v[16:17], v[130:131], v[128:129] neg_lo:[0,0,1] neg_hi:[0,0,1]
	v_pk_fma_f32 v[136:137], v[194:195], v[60:61], v[136:137]
	v_pk_fma_f32 v[134:135], v[196:197], v[130:131], v[134:135]
	v_cndmask_b32_e64 v0, v129, v131, s[12:13]
	v_cndmask_b32_e64 v128, v128, v130, s[12:13]
	v_cndmask_b32_e64 v61, v133, v61, s[12:13]
	v_cndmask_b32_e64 v60, v132, v60, s[12:13]
	v_cndmask_b32_e64 v129, v135, v59, s[12:13]
	v_cndmask_b32_e64 v130, v134, v58, s[12:13]
	v_cndmask_b32_e64 v127, v137, v127, s[12:13]
	v_cndmask_b32_e64 v126, v136, v126, s[12:13]
	v_cvt_pk_bf16_f32 v58, v60, v61
	v_cvt_pk_bf16_f32 v59, v128, v0
	v_cvt_pk_bf16_f32 v60, v126, v127
	v_cvt_pk_bf16_f32 v61, v130, v129
	v_add_u32_e32 v126, 0x80, v222
	s_and_b64 vcc, exec, s[8:9]
	global_store_dwordx4 v[138:139], v[58:61], off offset:256
	s_cbranch_vccnz .LBB0_890
	s_and_b64 vcc, s[44:45], exec
	v_and_b32_e32 v0, 0x7cf, v126
	s_cselect_b32 s63, 5, 4
	v_lshlrev_b32_e32 v0, s63, v0
	v_lshlrev_b32_e32 v0, 2, v0
	v_lshl_add_u64 v[2:3], v[218:219], 0, v[0:1]
	global_load_dwordx4 v[30:33], v[2:3], off
	v_lshl_add_u64 v[2:3], v[220:221], 0, v[0:1]
	global_load_dwordx4 v[166:169], v[2:3], off
	s_lshl_b32 s100, 64, s63
	s_mov_b32 s101, 0
	v_lshl_add_u64 v[4:5], v[218:219], 0, v[0:1]
	v_mov_b64_e32 v[6:7], v[2:3]
	v_lshl_add_u64 v[4:5], v[4:5], 0, s[100:101]
	v_lshl_add_u64 v[6:7], v[6:7], 0, s[100:101]
	global_load_dword v8, v[4:5], off
	global_load_dword v8, v[6:7], off
	v_lshl_add_u64 v[4:5], v[4:5], 0, s[100:101]
	v_lshl_add_u64 v[6:7], v[6:7], 0, s[100:101]
	global_load_dword v8, v[4:5], off
	global_load_dword v8, v[6:7], off
	v_lshl_add_u64 v[4:5], v[4:5], 0, s[100:101]
	v_lshl_add_u64 v[6:7], v[6:7], 0, s[100:101]
	global_load_dword v8, v[4:5], off
	global_load_dword v8, v[6:7], off
	s_waitcnt vmcnt(0)
	v_mov_b64_e32 v[60:61], v[44:45]
	v_mov_b64_e32 v[58:59], v[42:43]
	v_mov_b64_e32 v[56:57], v[40:41]
	v_mov_b64_e32 v[54:55], v[38:39]
	v_mov_b64_e32 v[52:53], v[36:37]
	v_mov_b64_e32 v[50:51], v[34:35]
	v_mov_b64_e32 v[2:3], v[30:31]
	v_mov_b64_e32 v[4:5], v[32:33]
	v_mov_b64_e32 v[6:7], v[34:35]
	v_mov_b64_e32 v[8:9], v[36:37]
	v_mov_b64_e32 v[10:11], v[38:39]
	v_mov_b64_e32 v[12:13], v[40:41]
	v_mov_b64_e32 v[14:15], v[42:43]
	v_mov_b64_e32 v[16:17], v[44:45]
	v_mov_b64_e32 v[48:49], v[32:33]
	v_mov_b64_e32 v[46:47], v[30:31]
	v_mov_b64_e32 v[18:19], v[30:31]
	v_mov_b64_e32 v[20:21], v[32:33]
	v_mov_b64_e32 v[22:23], v[34:35]
	v_mov_b64_e32 v[24:25], v[36:37]
	v_mov_b64_e32 v[26:27], v[38:39]
	v_mov_b64_e32 v[28:29], v[40:41]
	v_mov_b64_e32 v[30:31], v[42:43]
	v_mov_b64_e32 v[32:33], v[44:45]
.LBB0_890:
	v_mov_b64_e32 v[34:35], s[48:49]
	v_mad_i64_i32 v[34:35], vcc, v126, s76, v[34:35]
	global_load_dwordx4 v[58:61], v[34:35], off
	global_load_dwordx4 v[128:131], v[34:35], off offset:16
	global_load_dword v36, v[34:35], off offset:32
	global_load_dword v36, v[34:35], off offset:1280
	global_load_dword v36, v[34:35], off offset:1296
	global_load_dword v36, v[34:35], off offset:1312
	global_load_dword v36, v[34:35], off offset:2560
	global_load_dword v36, v[34:35], off offset:2576
	global_load_dword v36, v[34:35], off offset:2592
	global_load_dword v36, v[34:35], off offset:3840
	global_load_dword v36, v[34:35], off offset:3856
	global_load_dword v36, v[34:35], off offset:3872
	s_and_b64 vcc, exec, s[6:7]
	s_waitcnt vmcnt(0)
	v_mov_b32_e32 v36, v58
	v_mov_b32_e32 v37, v128
	v_mov_b32_e32 v128, v59
	v_mov_b32_e32 v58, v60
	v_mov_b32_e32 v59, v130
	v_mov_b32_e32 v130, v61
	v_pk_add_f32 v[36:37], v[36:37], v[128:129]
	v_pk_add_f32 v[58:59], v[58:59], v[130:131]
	s_nop 0
	v_pk_add_f32 v[36:37], v[36:37], v[58:59]
	s_nop 0
	v_pk_add_f32 v[36:37], v[36:37], v[36:37] op_sel:[0,1] op_sel_hi:[1,0]
	s_cbranch_vccnz .LBB0_892
	global_load_dwordx4 v[58:61], v[34:35], off offset:32
	s_waitcnt vmcnt(0)
	v_mov_b32_e32 v34, v59
	v_mov_b32_e32 v35, v60
	v_mov_b32_e32 v59, v61
	v_pk_add_f32 v[34:35], v[34:35], v[58:59]
	s_nop 0
	v_add_f32_e32 v0, v34, v35
	v_add_f32_e32 v36, v36, v0

.LBB0_959:
	v_pk_add_f32 v[34:35], v[122:123], v[122:123] op_sel:[0,1] op_sel_hi:[1,0]
	s_lshl_b64 s[4:5], s[10:11], 1
	v_mov_b32_e32 v0, v34
	s_nop 1
	v_permlane32_swap_b32_e32 v34, v0
	v_add_f32_e32 v0, v34, v0
	v_div_scale_f32 v34, s[8:9], v0, v0, 1.0
	v_rcp_f32_e32 v35, v34
	s_add_u32 s4, s80, s4
	s_addc_u32 s5, s83, s5
	s_lshl_b32 s6, s22, 7
	v_fma_f32 v36, -v34, v35, 1.0
	v_fmac_f32_e32 v35, v36, v35
	v_div_scale_f32 v36, vcc, 1.0, v0, 1.0
	v_mul_f32_e32 v37, v36, v35
	s_add_u32 s4, s4, s6
	v_fma_f32 v38, -v34, v37, v36
	s_addc_u32 s5, s5, 0
	v_fmac_f32_e32 v37, v38, v35
	s_add_u32 s6, s23, s6
	v_fma_f32 v34, -v34, v37, v36
	s_addc_u32 s7, s27, 0
	v_div_fmas_f32 v34, v34, v35, v37
	v_div_fixup_f32 v36, v34, v0, 1.0
	v_mov_b64_e32 v[34:35], s[6:7]
	v_mad_i64_i32 v[34:35], s[6:7], v106, s62, v[34:35]
	v_lshlrev_b32_e32 v0, 1, v113
	v_mul_f32_e32 v42, v20, v36
	v_mul_f32_e32 v43, v21, v36
	v_lshl_add_u64 v[20:21], v[34:35], 0, v[0:1]
	v_mul_f32_e32 v40, v22, v36
	v_mul_f32_e32 v41, v23, v36
	v_mul_f32_e32 v44, v24, v36
	v_mul_f32_e32 v45, v25, v36
	global_load_dwordx4 v[22:25], v[20:21], off offset:1536
	global_load_dwordx4 v[228:231], v[20:21], off offset:1568
	global_load_dwordx4 v[232:235], v[20:21], off offset:1600
	global_load_dwordx4 v[236:239], v[20:21], off offset:1632
	v_mul_f32_e32 v18, v18, v36
	v_mul_f32_e32 v19, v19, v36
	s_nop 0
	v_permlane32_swap_b32_e32 v18, v40
	v_permlane32_swap_b32_e32 v19, v41
	v_permlane32_swap_b32_e32 v42, v44
	v_permlane32_swap_b32_e32 v43, v45
	v_lshlrev_b64 v[38:39], 11, v[106:107]
	v_lshl_add_u64 v[38:39], s[4:5], 0, v[38:39]
	v_mul_f32_e32 v6, v6, v36
	v_mul_f32_e32 v7, v7, v36
	v_mul_f32_e32 v4, v4, v36
	v_mul_f32_e32 v5, v5, v36
	s_waitcnt vmcnt(3)
	v_lshlrev_b32_e32 v34, 16, v22
	v_and_b32_e32 v35, 0xffff0000, v22
	v_mul_f32_e32 v22, 0xbfb8aa3b, v34
	v_exp_f32_e32 v22, v22
	s_nop 0
	v_add_f32_e32 v22, 1.0, v22
	v_rcp_f32_e32 v46, v22
	v_mul_f32_e32 v22, 0xbfb8aa3b, v35
	v_exp_f32_e32 v22, v22
	s_nop 0
	v_add_f32_e32 v22, 1.0, v22
	v_rcp_f32_e32 v47, v22
	v_lshlrev_b32_e32 v22, 16, v23
	v_and_b32_e32 v23, 0xffff0000, v23
	v_pk_mul_f32 v[34:35], v[46:47], v[34:35]
	s_nop 0
	v_pk_mul_f32 v[18:19], v[34:35], v[18:19]
	v_mul_f32_e32 v34, 0xbfb8aa3b, v22
	v_mul_f32_e32 v35, 0xbfb8aa3b, v23
	v_exp_f32_e32 v34, v34
	v_exp_f32_e32 v35, v35
	v_add_f32_e32 v34, 1.0, v34
	v_add_f32_e32 v35, 1.0, v35
	v_rcp_f32_e32 v34, v34
	v_rcp_f32_e32 v35, v35
	s_nop 0
	v_pk_mul_f32 v[22:23], v[34:35], v[22:23]
	s_nop 0
	v_pk_mul_f32 v[34:35], v[22:23], v[42:43]
	v_lshlrev_b32_e32 v22, 16, v24
	v_and_b32_e32 v23, 0xffff0000, v24
	v_mul_f32_e32 v24, 0xbfb8aa3b, v22
	v_exp_f32_e32 v24, v24
	s_nop 0
	v_add_f32_e32 v24, 1.0, v24
	v_rcp_f32_e32 v42, v24
	v_mul_f32_e32 v24, 0xbfb8aa3b, v23
	v_exp_f32_e32 v24, v24
	s_nop 0
	v_add_f32_e32 v24, 1.0, v24
	v_rcp_f32_e32 v43, v24
	s_nop 0
	v_pk_mul_f32 v[22:23], v[42:43], v[22:23]
	s_nop 0
	v_pk_mul_f32 v[40:41], v[22:23], v[40:41]
	v_lshlrev_b32_e32 v22, 16, v25
	v_and_b32_e32 v23, 0xffff0000, v25
	v_mul_f32_e32 v24, 0xbfb8aa3b, v22
	v_mul_f32_e32 v25, 0xbfb8aa3b, v23
	v_exp_f32_e32 v24, v24
	v_exp_f32_e32 v25, v25
	v_add_f32_e32 v24, 1.0, v24
	v_add_f32_e32 v25, 1.0, v25
	v_rcp_f32_e32 v24, v24
	v_rcp_f32_e32 v25, v25
	s_nop 0
	v_pk_mul_f32 v[22:23], v[24:25], v[22:23]
	s_nop 0
	v_pk_mul_f32 v[42:43], v[22:23], v[44:45]
	v_cvt_pk_bf16_f32 v22, v18, v19
	v_cvt_pk_bf16_f32 v23, v34, v35
	v_cvt_pk_bf16_f32 v24, v40, v41
	v_cvt_pk_bf16_f32 v25, v42, v43
	v_lshl_add_u64 v[18:19], v[38:39], 0, v[0:1]
	global_store_dwordx4 v[18:19], v[22:25], off
	v_mul_f32_e32 v34, v26, v36
	v_mul_f32_e32 v35, v27, v36
	v_mul_f32_e32 v24, v30, v36
	v_mul_f32_e32 v25, v31, v36
	v_mul_f32_e32 v26, v28, v36
	v_mul_f32_e32 v27, v29, v36
	s_nop 0
	v_mul_f32_e32 v22, v32, v36
	v_mul_f32_e32 v23, v33, v36
	v_permlane32_swap_b32_e32 v34, v24
	v_permlane32_swap_b32_e32 v35, v25
	v_permlane32_swap_b32_e32 v26, v22
	v_permlane32_swap_b32_e32 v27, v23
	s_waitcnt vmcnt(3)
	v_mov_b32_e32 v28, v228
	v_mov_b32_e32 v29, v229
	v_mov_b32_e32 v30, v230
	v_mov_b32_e32 v31, v231
	v_lshlrev_b32_e32 v32, 16, v28
	v_mul_f32_e32 v0, 0xbfb8aa3b, v32
	v_exp_f32_e32 v0, v0
	v_and_b32_e32 v33, 0xffff0000, v28
	v_lshlrev_b32_e32 v28, 16, v29
	v_and_b32_e32 v29, 0xffff0000, v29
	v_add_f32_e32 v0, 1.0, v0
	v_rcp_f32_e32 v38, v0
	v_mul_f32_e32 v0, 0xbfb8aa3b, v33
	v_exp_f32_e32 v0, v0
	s_nop 0
	v_add_f32_e32 v0, 1.0, v0
	v_rcp_f32_e32 v39, v0
	v_mul_f32_e32 v0, 0xbfb8aa3b, v28
	v_exp_f32_e32 v0, v0
	v_pk_mul_f32 v[32:33], v[38:39], v[32:33]
	s_nop 0
	v_pk_mul_f32 v[32:33], v[32:33], v[34:35]
	v_add_f32_e32 v0, 1.0, v0
	v_rcp_f32_e32 v34, v0
	v_mul_f32_e32 v0, 0xbfb8aa3b, v29
	v_exp_f32_e32 v0, v0
	s_nop 0
	v_add_f32_e32 v0, 1.0, v0
	v_rcp_f32_e32 v35, v0
	s_nop 0
	v_pk_mul_f32 v[28:29], v[34:35], v[28:29]
	s_nop 0
	v_pk_mul_f32 v[26:27], v[28:29], v[26:27]
	v_lshlrev_b32_e32 v28, 16, v30
	v_mul_f32_e32 v0, 0xbfb8aa3b, v28
	v_exp_f32_e32 v0, v0
	v_and_b32_e32 v29, 0xffff0000, v30
	v_add_f32_e32 v0, 1.0, v0
	v_rcp_f32_e32 v34, v0
	v_mul_f32_e32 v0, 0xbfb8aa3b, v29
	v_exp_f32_e32 v0, v0
	s_nop 0
	v_add_f32_e32 v0, 1.0, v0
	v_rcp_f32_e32 v35, v0
	s_nop 0
	v_pk_mul_f32 v[28:29], v[34:35], v[28:29]
	s_nop 0
	v_pk_mul_f32 v[24:25], v[28:29], v[24:25]
	v_lshlrev_b32_e32 v28, 16, v31
	v_mul_f32_e32 v0, 0xbfb8aa3b, v28
	v_exp_f32_e32 v0, v0
	v_and_b32_e32 v29, 0xffff0000, v31
	v_cvt_pk_bf16_f32 v24, v24, v25
	v_add_f32_e32 v0, 1.0, v0
	v_rcp_f32_e32 v30, v0
	v_mul_f32_e32 v0, 0xbfb8aa3b, v29
	v_exp_f32_e32 v0, v0
	s_nop 0
	v_add_f32_e32 v0, 1.0, v0
	v_rcp_f32_e32 v31, v0
	s_nop 0
	v_pk_mul_f32 v[28:29], v[30:31], v[28:29]
	s_nop 0
	v_pk_mul_f32 v[28:29], v[28:29], v[22:23]
	v_cvt_pk_bf16_f32 v22, v32, v33
	v_cvt_pk_bf16_f32 v23, v26, v27
	v_cvt_pk_bf16_f32 v25, v28, v29
	global_store_dwordx4 v[18:19], v[22:25], off offset:32
	s_nop 0
	s_nop 0
	v_mul_f32_e32 v22, v2, v36
	v_mul_f32_e32 v2, v8, v36
	v_mul_f32_e32 v23, v3, v36
	v_mul_f32_e32 v3, v9, v36
	v_permlane32_swap_b32_e32 v22, v6
	v_permlane32_swap_b32_e32 v23, v7
	v_permlane32_swap_b32_e32 v4, v2
	v_permlane32_swap_b32_e32 v5, v3
	s_waitcnt vmcnt(3)
	v_mov_b32_e32 v24, v232
	v_mov_b32_e32 v25, v233
	v_mov_b32_e32 v26, v234
	v_mov_b32_e32 v27, v235
	v_lshlrev_b32_e32 v8, 16, v24
	v_mul_f32_e32 v0, 0xbfb8aa3b, v8
	v_exp_f32_e32 v0, v0
	v_and_b32_e32 v9, 0xffff0000, v24
	v_add_f32_e32 v0, 1.0, v0
	v_rcp_f32_e32 v28, v0
	v_mul_f32_e32 v0, 0xbfb8aa3b, v9
	v_exp_f32_e32 v0, v0
	s_nop 0
	v_add_f32_e32 v0, 1.0, v0
	v_rcp_f32_e32 v29, v0
	s_nop 0
	v_pk_mul_f32 v[8:9], v[28:29], v[8:9]
	s_nop 0
	v_pk_mul_f32 v[8:9], v[8:9], v[22:23]
	v_lshlrev_b32_e32 v22, 16, v25
	v_mul_f32_e32 v0, 0xbfb8aa3b, v22
	v_exp_f32_e32 v0, v0
	v_and_b32_e32 v23, 0xffff0000, v25
	v_add_f32_e32 v0, 1.0, v0
	v_rcp_f32_e32 v24, v0
	v_mul_f32_e32 v0, 0xbfb8aa3b, v23
	v_exp_f32_e32 v0, v0
	s_nop 0
	v_add_f32_e32 v0, 1.0, v0
	v_rcp_f32_e32 v25, v0
	s_nop 0
	v_pk_mul_f32 v[22:23], v[24:25], v[22:23]
	s_nop 0
	v_pk_mul_f32 v[4:5], v[22:23], v[4:5]
	v_lshlrev_b32_e32 v22, 16, v26
	v_mul_f32_e32 v0, 0xbfb8aa3b, v22
	v_exp_f32_e32 v0, v0
	v_and_b32_e32 v23, 0xffff0000, v26
	v_add_f32_e32 v0, 1.0, v0
	v_rcp_f32_e32 v24, v0
	v_mul_f32_e32 v0, 0xbfb8aa3b, v23
	v_exp_f32_e32 v0, v0
	s_nop 0
	v_add_f32_e32 v0, 1.0, v0
	v_rcp_f32_e32 v25, v0
	s_nop 0
	v_pk_mul_f32 v[22:23], v[24:25], v[22:23]
	s_nop 0
	v_pk_mul_f32 v[6:7], v[22:23], v[6:7]
	v_lshlrev_b32_e32 v22, 16, v27
	v_mul_f32_e32 v0, 0xbfb8aa3b, v22
	v_exp_f32_e32 v0, v0
	v_and_b32_e32 v23, 0xffff0000, v27
	v_add_f32_e32 v0, 1.0, v0
	v_rcp_f32_e32 v24, v0
	v_mul_f32_e32 v0, 0xbfb8aa3b, v23
	v_exp_f32_e32 v0, v0
	s_nop 0
	v_add_f32_e32 v0, 1.0, v0
	v_rcp_f32_e32 v25, v0
	s_nop 0
	v_pk_mul_f32 v[22:23], v[24:25], v[22:23]
	s_nop 0
	v_pk_mul_f32 v[22:23], v[22:23], v[2:3]
	v_cvt_pk_bf16_f32 v2, v8, v9
	v_cvt_pk_bf16_f32 v3, v4, v5
	v_cvt_pk_bf16_f32 v4, v6, v7
	v_cvt_pk_bf16_f32 v5, v22, v23
	global_store_dwordx4 v[18:19], v[2:5], off offset:64
	s_nop 0
	v_mul_f32_e32 v22, v10, v36
	v_mul_f32_e32 v10, v12, v36
	v_mul_f32_e32 v23, v11, v36
	v_mul_f32_e32 v11, v13, v36
	v_mul_f32_e32 v8, v14, v36
	v_mul_f32_e32 v9, v15, v36
	v_mul_f32_e32 v6, v16, v36
	v_mul_f32_e32 v7, v17, v36
	s_nop 0
	v_permlane32_swap_b32_e32 v10, v6
	v_permlane32_swap_b32_e32 v11, v7
	v_permlane32_swap_b32_e32 v22, v8
	v_permlane32_swap_b32_e32 v23, v9
	s_waitcnt vmcnt(3)
	v_mov_b32_e32 v2, v236
	v_mov_b32_e32 v3, v237
	v_mov_b32_e32 v4, v238
	v_mov_b32_e32 v5, v239
	v_lshlrev_b32_e32 v12, 16, v2
	v_mul_f32_e32 v0, 0xbfb8aa3b, v12
	v_exp_f32_e32 v0, v0
	v_and_b32_e32 v13, 0xffff0000, v2
	v_lshlrev_b32_e32 v2, 16, v3
	v_and_b32_e32 v3, 0xffff0000, v3
	v_add_f32_e32 v0, 1.0, v0
	v_rcp_f32_e32 v14, v0
	v_mul_f32_e32 v0, 0xbfb8aa3b, v13
	v_exp_f32_e32 v0, v0
	s_nop 0
	v_add_f32_e32 v0, 1.0, v0
	v_rcp_f32_e32 v15, v0
	v_mul_f32_e32 v0, 0xbfb8aa3b, v2
	v_exp_f32_e32 v0, v0
	v_pk_mul_f32 v[12:13], v[14:15], v[12:13]
	s_nop 0
	v_pk_mul_f32 v[12:13], v[12:13], v[22:23]
	v_add_f32_e32 v0, 1.0, v0
	v_rcp_f32_e32 v14, v0
	v_mul_f32_e32 v0, 0xbfb8aa3b, v3
	v_exp_f32_e32 v0, v0
	s_nop 0
	v_add_f32_e32 v0, 1.0, v0
	v_rcp_f32_e32 v15, v0
	s_nop 0
	v_pk_mul_f32 v[2:3], v[14:15], v[2:3]
	s_nop 0
	v_pk_mul_f32 v[10:11], v[2:3], v[10:11]
	v_lshlrev_b32_e32 v2, 16, v4
	v_mul_f32_e32 v0, 0xbfb8aa3b, v2
	v_exp_f32_e32 v0, v0
	v_and_b32_e32 v3, 0xffff0000, v4
	v_add_f32_e32 v0, 1.0, v0
	v_rcp_f32_e32 v14, v0
	v_mul_f32_e32 v0, 0xbfb8aa3b, v3
	v_exp_f32_e32 v0, v0
	s_nop 0
	v_add_f32_e32 v0, 1.0, v0
	v_rcp_f32_e32 v15, v0
	s_nop 0
	v_pk_mul_f32 v[2:3], v[14:15], v[2:3]
	s_nop 0
	v_pk_mul_f32 v[8:9], v[2:3], v[8:9]
	v_lshlrev_b32_e32 v2, 16, v5
	v_mul_f32_e32 v0, 0xbfb8aa3b, v2
	v_exp_f32_e32 v0, v0
	v_and_b32_e32 v3, 0xffff0000, v5
	v_add_f32_e32 v0, 1.0, v0
	v_rcp_f32_e32 v4, v0
	v_mul_f32_e32 v0, 0xbfb8aa3b, v3
	v_exp_f32_e32 v0, v0
	s_nop 0
	v_add_f32_e32 v0, 1.0, v0
	v_rcp_f32_e32 v5, v0
	s_nop 0
	v_pk_mul_f32 v[2:3], v[4:5], v[2:3]
	s_nop 0
	v_pk_mul_f32 v[6:7], v[2:3], v[6:7]
	v_cvt_pk_bf16_f32 v2, v12, v13
	v_cvt_pk_bf16_f32 v3, v10, v11
	v_cvt_pk_bf16_f32 v4, v8, v9
	v_cvt_pk_bf16_f32 v5, v6, v7
	global_store_dwordx4 v[18:19], v[2:5], off offset:96

	.amdhsa_kernel _Z14fwd_megakernel6Params
		.amdhsa_group_segment_fixed_size 0
		.amdhsa_private_segment_fixed_size 0
		.amdhsa_kernarg_size 416
		.amdhsa_user_sgpr_count 2
		.amdhsa_user_sgpr_dispatch_ptr 0
		.amdhsa_user_sgpr_queue_ptr 0
		.amdhsa_user_sgpr_kernarg_segment_ptr 1
		.amdhsa_user_sgpr_dispatch_id 0
		.amdhsa_user_sgpr_kernarg_preload_length 0
		.amdhsa_user_sgpr_kernarg_preload_offset 0
		.amdhsa_user_sgpr_private_segment_size 0
		.amdhsa_uses_dynamic_stack 0
		.amdhsa_enable_private_segment 0
		.amdhsa_system_sgpr_workgroup_id_x 1
		.amdhsa_system_sgpr_workgroup_id_y 0
		.amdhsa_system_sgpr_workgroup_id_z 0
		.amdhsa_system_sgpr_workgroup_info 0
		.amdhsa_system_vgpr_workitem_id 2
		.amdhsa_next_free_vgpr 256
		.amdhsa_next_free_sgpr 102
		.amdhsa_accum_offset 256
		.amdhsa_reserve_vcc 1
		.amdhsa_float_round_mode_32 0
		.amdhsa_float_round_mode_16_64 0
		.amdhsa_float_denorm_mode_32 3
		.amdhsa_float_denorm_mode_16_64 3
		.amdhsa_dx10_clamp 1
		.amdhsa_ieee_mode 1
		.amdhsa_fp16_overflow 0
		.amdhsa_tg_split 0
		.amdhsa_exception_fp_ieee_invalid_op 0
		.amdhsa_exception_fp_denorm_src 0
		.amdhsa_exception_fp_ieee_div_zero 0
		.amdhsa_exception_fp_ieee_overflow 0
		.amdhsa_exception_fp_ieee_underflow 0
		.amdhsa_exception_fp_ieee_inexact 0
		.amdhsa_exception_int_div_zero 0
	.end_amdhsa_kernel

amdhsa.kernels:
  - .agpr_count:     0
    .args:
      - .offset:         0
        .size:           160
        .value_kind:     by_value
      - .offset:         160
        .size:           4
        .value_kind:     hidden_block_count_x
      - .offset:         164
        .size:           4
        .value_kind:     hidden_block_count_y
      - .offset:         168
        .size:           4
        .value_kind:     hidden_block_count_z
      - .offset:         172
        .size:           2
        .value_kind:     hidden_group_size_x
      - .offset:         174
        .size:           2
        .value_kind:     hidden_group_size_y
      - .offset:         176
        .size:           2
        .value_kind:     hidden_group_size_z
      - .offset:         178
        .size:           2
        .value_kind:     hidden_remainder_x
      - .offset:         180
        .size:           2
        .value_kind:     hidden_remainder_y
      - .offset:         182
        .size:           2
        .value_kind:     hidden_remainder_z
      - .offset:         200
        .size:           8
        .value_kind:     hidden_global_offset_x
      - .offset:         208
        .size:           8
        .value_kind:     hidden_global_offset_y
      - .offset:         216
        .size:           8
        .value_kind:     hidden_global_offset_z
      - .offset:         224
        .size:           2
        .value_kind:     hidden_grid_dims
      - .offset:         248
        .size:           8
        .value_kind:     hidden_multigrid_sync_arg
      - .offset:         280
        .size:           4
        .value_kind:     hidden_dynamic_lds_size
    .group_segment_fixed_size: 0
    .kernarg_segment_align: 8
    .kernarg_segment_size: 416
    .language:       OpenCL C
    .language_version:
      - 2
      - 0
    .max_flat_workgroup_size: 512
    .name:           _Z14fwd_megakernel6Params
    .private_segment_fixed_size: 0
    .sgpr_count:     108
    .sgpr_spill_count: 163
    .symbol:         _Z14fwd_megakernel6Params.kd
    .uniform_work_group_size: 1
    .uses_dynamic_stack: false
    .vgpr_count:     256
    .vgpr_spill_count: 0
    .wavefront_size: 64
